# P5 K-loop: LDS-DMA source addresses formed on the SALU (SGPR base + 32-bit lane offset) instead of 16 64-bit VALU adds per iteration; rest as best
# speedup vs baseline: 1.0034x; 1.0004x over previous
.LBB0_507:
	ds_read_b128 v[166:169], v163
	ds_read_b128 v[170:173], v163 offset:1024
	ds_read_b128 v[174:177], v163 offset:2048
	ds_read_b128 v[178:181], v163 offset:3072
	ds_read_b128 v[182:185], v164
	ds_read_b128 v[188:191], v164 offset:1024
	ds_read_b128 v[192:195], v164 offset:2048
	ds_read_b128 v[196:199], v164 offset:3072
	s_add_u32 s44, s42, 0xfff80080
	s_addc_u32 s45, s43, -1
	s_cmp_eq_u32 s52, 28
	s_cselect_b32 s47, s7, s45
	s_cselect_b32 s46, s6, s44
	s_cselect_b32 s45, s23, s21
	s_cselect_b32 s44, s22, s17
	s_add_u32 s54, s44, 0x80000
	s_addc_u32 s55, s45, 0
	s_mov_b32 m0, s94
	ds_read_b128 v[200:203], v165
	ds_read_b128 v[204:207], v165 offset:1024
	ds_read_b128 v[208:211], v165 offset:2048
	ds_read_b128 v[212:215], v165 offset:3072
	ds_read_b128 v[216:219], v165 offset:4096
	ds_read_b128 v[220:223], v165 offset:5120
	ds_read_b128 v[224:227], v165 offset:6144
	ds_read_b128 v[228:231], v165 offset:7168
	global_load_lds_dwordx4 v152, s[42:43]
	s_mov_b32 m0, s95
	s_nop 0
	global_load_lds_dwordx4 v154, s[42:43]
	s_waitcnt vmcnt(8)
	s_waitcnt lgkmcnt(0)
	s_barrier
	s_setprio 1
	s_waitcnt lgkmcnt(0)
	v_mfma_f32_16x16x32_bf16 v[124:127], v[166:169], v[200:203], v[124:127]
	v_mfma_f32_16x16x32_bf16 v[120:123], v[174:177], v[200:203], v[120:123]
	v_mfma_f32_16x16x32_bf16 v[108:111], v[166:169], v[208:211], v[108:111]
	v_mfma_f32_16x16x32_bf16 v[104:107], v[174:177], v[208:211], v[104:107]
	v_mfma_f32_16x16x32_bf16 v[92:95], v[166:169], v[216:219], v[92:95]
	v_mfma_f32_16x16x32_bf16 v[88:91], v[174:177], v[216:219], v[88:91]
	v_mfma_f32_16x16x32_bf16 v[76:79], v[166:169], v[224:227], v[76:79]
	v_mfma_f32_16x16x32_bf16 v[72:75], v[174:177], v[224:227], v[72:75]
	v_mfma_f32_16x16x32_bf16 v[124:127], v[170:173], v[204:207], v[124:127]
	v_mfma_f32_16x16x32_bf16 v[120:123], v[178:181], v[204:207], v[120:123]
	v_mfma_f32_16x16x32_bf16 v[108:111], v[170:173], v[212:215], v[108:111]
	v_mfma_f32_16x16x32_bf16 v[104:107], v[178:181], v[212:215], v[104:107]
	v_mfma_f32_16x16x32_bf16 v[92:95], v[170:173], v[220:223], v[92:95]
	v_mfma_f32_16x16x32_bf16 v[88:91], v[178:181], v[220:223], v[88:91]
	v_mfma_f32_16x16x32_bf16 v[76:79], v[170:173], v[228:231], v[76:79]
	v_mfma_f32_16x16x32_bf16 v[72:75], v[178:181], v[228:231], v[72:75]
	s_setprio 0
	s_setprio 1
	v_mfma_f32_16x16x32_bf16 v[116:119], v[182:185], v[200:203], v[116:119]
	v_mfma_f32_16x16x32_bf16 v[112:115], v[192:195], v[200:203], v[112:115]
	v_mfma_f32_16x16x32_bf16 v[100:103], v[182:185], v[208:211], v[100:103]
	v_mfma_f32_16x16x32_bf16 v[96:99], v[192:195], v[208:211], v[96:99]
	v_mfma_f32_16x16x32_bf16 v[84:87], v[182:185], v[216:219], v[84:87]
	v_mfma_f32_16x16x32_bf16 v[80:83], v[192:195], v[216:219], v[80:83]
	v_mfma_f32_16x16x32_bf16 v[68:71], v[182:185], v[224:227], v[68:71]
	v_mfma_f32_16x16x32_bf16 v[64:67], v[192:195], v[224:227], v[64:67]
	v_mfma_f32_16x16x32_bf16 v[116:119], v[188:191], v[204:207], v[116:119]
	v_mfma_f32_16x16x32_bf16 v[112:115], v[196:199], v[204:207], v[112:115]
	v_mfma_f32_16x16x32_bf16 v[100:103], v[188:191], v[212:215], v[100:103]
	v_mfma_f32_16x16x32_bf16 v[96:99], v[196:199], v[212:215], v[96:99]
	v_mfma_f32_16x16x32_bf16 v[84:87], v[188:191], v[220:223], v[84:87]
	v_mfma_f32_16x16x32_bf16 v[80:83], v[196:199], v[220:223], v[80:83]
	v_mfma_f32_16x16x32_bf16 v[68:71], v[188:191], v[228:231], v[68:71]
	v_mfma_f32_16x16x32_bf16 v[64:67], v[196:199], v[228:231], v[64:67]
	s_setprio 0
	s_barrier
	s_mov_b32 m0, s96
	s_add_u32 s98, s46, 0x80000
	s_addc_u32 s99, s47, 0
	ds_read_b128 v[200:203], v165 offset:16384
	ds_read_b128 v[204:207], v165 offset:17408
	ds_read_b128 v[208:211], v165 offset:18432
	ds_read_b128 v[212:215], v165 offset:19456
	ds_read_b128 v[216:219], v165 offset:20480
	ds_read_b128 v[220:223], v165 offset:21504
	ds_read_b128 v[224:227], v165 offset:22528
	ds_read_b128 v[228:231], v165 offset:23552
	global_load_lds_dwordx4 v130, s[44:45]
	s_mov_b32 m0, s97
	s_nop 0
	global_load_lds_dwordx4 v134, s[44:45]
	s_mov_b32 m0, s91
	s_nop 0
	global_load_lds_dwordx4 v130, s[54:55]
	s_mov_b32 m0, s26
	s_nop 0
	global_load_lds_dwordx4 v134, s[54:55]
	s_mov_b32 m0, s33
	s_nop 0
	global_load_lds_dwordx4 v128, s[46:47]
	s_mov_b32 m0, s88
	s_nop 0
	global_load_lds_dwordx4 v132, s[46:47]
	s_waitcnt vmcnt(8)
	s_waitcnt lgkmcnt(0)
	s_barrier
	s_setprio 1
	s_waitcnt lgkmcnt(0)
	v_mfma_f32_16x16x32_bf16 v[60:63], v[166:169], v[200:203], v[60:63]
	v_mfma_f32_16x16x32_bf16 v[56:59], v[174:177], v[200:203], v[56:59]
	v_mfma_f32_16x16x32_bf16 v[44:47], v[166:169], v[208:211], v[44:47]
	v_mfma_f32_16x16x32_bf16 v[40:43], v[174:177], v[208:211], v[40:43]
	v_mfma_f32_16x16x32_bf16 v[28:31], v[166:169], v[216:219], v[28:31]
	v_mfma_f32_16x16x32_bf16 v[24:27], v[174:177], v[216:219], v[24:27]
	v_mfma_f32_16x16x32_bf16 v[12:15], v[166:169], v[224:227], v[12:15]
	v_mfma_f32_16x16x32_bf16 v[8:11], v[174:177], v[224:227], v[8:11]
	v_mfma_f32_16x16x32_bf16 v[60:63], v[170:173], v[204:207], v[60:63]
	v_mfma_f32_16x16x32_bf16 v[56:59], v[178:181], v[204:207], v[56:59]
	v_mfma_f32_16x16x32_bf16 v[44:47], v[170:173], v[212:215], v[44:47]
	v_mfma_f32_16x16x32_bf16 v[40:43], v[178:181], v[212:215], v[40:43]
	v_mfma_f32_16x16x32_bf16 v[28:31], v[170:173], v[220:223], v[28:31]
	v_mfma_f32_16x16x32_bf16 v[24:27], v[178:181], v[220:223], v[24:27]
	v_mfma_f32_16x16x32_bf16 v[12:15], v[170:173], v[228:231], v[12:15]
	v_mfma_f32_16x16x32_bf16 v[8:11], v[178:181], v[228:231], v[8:11]
	s_setprio 0
	s_setprio 1
	v_mfma_f32_16x16x32_bf16 v[52:55], v[182:185], v[200:203], v[52:55]
	v_mfma_f32_16x16x32_bf16 v[48:51], v[192:195], v[200:203], v[48:51]
	v_mfma_f32_16x16x32_bf16 v[36:39], v[182:185], v[208:211], v[36:39]
	v_mfma_f32_16x16x32_bf16 v[32:35], v[192:195], v[208:211], v[32:35]
	v_mfma_f32_16x16x32_bf16 v[20:23], v[182:185], v[216:219], v[20:23]
	v_mfma_f32_16x16x32_bf16 v[16:19], v[192:195], v[216:219], v[16:19]
	v_mfma_f32_16x16x32_bf16 v[4:7], v[182:185], v[224:227], v[4:7]
	v_mfma_f32_16x16x32_bf16 v[0:3], v[192:195], v[224:227], v[0:3]
	v_mfma_f32_16x16x32_bf16 v[52:55], v[188:191], v[204:207], v[52:55]
	v_mfma_f32_16x16x32_bf16 v[48:51], v[196:199], v[204:207], v[48:51]
	v_mfma_f32_16x16x32_bf16 v[36:39], v[188:191], v[212:215], v[36:39]
	v_mfma_f32_16x16x32_bf16 v[32:35], v[196:199], v[212:215], v[32:35]
	v_mfma_f32_16x16x32_bf16 v[20:23], v[188:191], v[220:223], v[20:23]
	v_mfma_f32_16x16x32_bf16 v[16:19], v[196:199], v[220:223], v[16:19]
	v_mfma_f32_16x16x32_bf16 v[4:7], v[188:191], v[228:231], v[4:7]
	v_mfma_f32_16x16x32_bf16 v[0:3], v[196:199], v[228:231], v[0:3]
	s_setprio 0
	s_barrier
	v_add_u32_e32 v178, s29, v162
	v_add_u32_e32 v187, s41, v162
	ds_read_b128 v[166:169], v178
	ds_read_b128 v[170:173], v178 offset:1024
	ds_read_b128 v[174:177], v178 offset:2048
	ds_read_b128 v[178:181], v178 offset:3072
	ds_read_b128 v[182:185], v187
	ds_read_b128 v[188:191], v187 offset:1024
	ds_read_b128 v[192:195], v187 offset:2048
	ds_read_b128 v[196:199], v187 offset:3072
	s_mov_b32 m0, s89
	s_add_u32 s100, s44, 0x80
	s_addc_u32 s101, s45, 0
	ds_read_b128 v[200:203], v165 offset:32768
	ds_read_b128 v[204:207], v165 offset:33792
	ds_read_b128 v[208:211], v165 offset:34816
	ds_read_b128 v[212:215], v165 offset:35840
	ds_read_b128 v[216:219], v165 offset:36864
	ds_read_b128 v[220:223], v165 offset:37888
	ds_read_b128 v[224:227], v165 offset:38912
	ds_read_b128 v[228:231], v165 offset:39936
	global_load_lds_dwordx4 v128, s[98:99]
	s_mov_b32 m0, s90
	s_add_u32 s54, s44, 0x80080
	s_addc_u32 s55, s45, 0
	global_load_lds_dwordx4 v132, s[98:99]
	s_add_u32 s98, s46, 0x80
	s_addc_u32 s99, s47, 0
	s_waitcnt vmcnt(8)
	s_waitcnt lgkmcnt(0)
	s_barrier
	s_setprio 1
	s_waitcnt lgkmcnt(0)
	v_mfma_f32_16x16x32_bf16 v[124:127], v[166:169], v[200:203], v[124:127]
	v_mfma_f32_16x16x32_bf16 v[120:123], v[174:177], v[200:203], v[120:123]
	v_mfma_f32_16x16x32_bf16 v[108:111], v[166:169], v[208:211], v[108:111]
	v_mfma_f32_16x16x32_bf16 v[104:107], v[174:177], v[208:211], v[104:107]
	v_mfma_f32_16x16x32_bf16 v[92:95], v[166:169], v[216:219], v[92:95]
	v_mfma_f32_16x16x32_bf16 v[88:91], v[174:177], v[216:219], v[88:91]
	v_mfma_f32_16x16x32_bf16 v[76:79], v[166:169], v[224:227], v[76:79]
	v_mfma_f32_16x16x32_bf16 v[72:75], v[174:177], v[224:227], v[72:75]
	v_mfma_f32_16x16x32_bf16 v[124:127], v[170:173], v[204:207], v[124:127]
	v_mfma_f32_16x16x32_bf16 v[120:123], v[178:181], v[204:207], v[120:123]
	v_mfma_f32_16x16x32_bf16 v[108:111], v[170:173], v[212:215], v[108:111]
	v_mfma_f32_16x16x32_bf16 v[104:107], v[178:181], v[212:215], v[104:107]
	v_mfma_f32_16x16x32_bf16 v[92:95], v[170:173], v[220:223], v[92:95]
	v_mfma_f32_16x16x32_bf16 v[88:91], v[178:181], v[220:223], v[88:91]
	v_mfma_f32_16x16x32_bf16 v[76:79], v[170:173], v[228:231], v[76:79]
	v_mfma_f32_16x16x32_bf16 v[72:75], v[178:181], v[228:231], v[72:75]
	s_setprio 0
	s_setprio 1
	v_mfma_f32_16x16x32_bf16 v[116:119], v[182:185], v[200:203], v[116:119]
	v_mfma_f32_16x16x32_bf16 v[112:115], v[192:195], v[200:203], v[112:115]
	v_mfma_f32_16x16x32_bf16 v[100:103], v[182:185], v[208:211], v[100:103]
	v_mfma_f32_16x16x32_bf16 v[96:99], v[192:195], v[208:211], v[96:99]
	v_mfma_f32_16x16x32_bf16 v[84:87], v[182:185], v[216:219], v[84:87]
	v_mfma_f32_16x16x32_bf16 v[80:83], v[192:195], v[216:219], v[80:83]
	v_mfma_f32_16x16x32_bf16 v[68:71], v[182:185], v[224:227], v[68:71]
	v_mfma_f32_16x16x32_bf16 v[64:67], v[192:195], v[224:227], v[64:67]
	v_mfma_f32_16x16x32_bf16 v[116:119], v[188:191], v[204:207], v[116:119]
	v_mfma_f32_16x16x32_bf16 v[112:115], v[196:199], v[204:207], v[112:115]
	v_mfma_f32_16x16x32_bf16 v[100:103], v[188:191], v[212:215], v[100:103]
	v_mfma_f32_16x16x32_bf16 v[96:99], v[196:199], v[212:215], v[96:99]
	v_mfma_f32_16x16x32_bf16 v[84:87], v[188:191], v[220:223], v[84:87]
	v_mfma_f32_16x16x32_bf16 v[80:83], v[196:199], v[220:223], v[80:83]
	v_mfma_f32_16x16x32_bf16 v[68:71], v[188:191], v[228:231], v[68:71]
	v_mfma_f32_16x16x32_bf16 v[64:67], v[196:199], v[228:231], v[64:67]
	s_setprio 0
	s_barrier
	s_mov_b32 m0, s27
	s_nop 0
	ds_read_b128 v[200:203], v165 offset:49152
	ds_read_b128 v[204:207], v165 offset:50176
	ds_read_b128 v[208:211], v165 offset:51200
	ds_read_b128 v[212:215], v165 offset:52224
	ds_read_b128 v[216:219], v165 offset:53248
	ds_read_b128 v[220:223], v165 offset:54272
	ds_read_b128 v[224:227], v165 offset:55296
	ds_read_b128 v[228:231], v165 offset:56320
	global_load_lds_dwordx4 v130, s[100:101]
	s_mov_b32 m0, s34
	s_nop 0
	global_load_lds_dwordx4 v134, s[100:101]
	s_mov_b32 m0, s35
	s_nop 0
	global_load_lds_dwordx4 v130, s[54:55]
	s_mov_b32 m0, s28
	s_nop 0
	global_load_lds_dwordx4 v134, s[54:55]
	s_mov_b32 m0, s92
	s_nop 0
	global_load_lds_dwordx4 v128, s[98:99]
	s_mov_b32 m0, s93
	s_nop 0
	global_load_lds_dwordx4 v132, s[98:99]
	s_waitcnt vmcnt(8)
	s_waitcnt lgkmcnt(0)
	s_barrier
	s_setprio 1
	s_waitcnt lgkmcnt(0)
	v_mfma_f32_16x16x32_bf16 v[60:63], v[166:169], v[200:203], v[60:63]
	v_mfma_f32_16x16x32_bf16 v[56:59], v[174:177], v[200:203], v[56:59]
	v_mfma_f32_16x16x32_bf16 v[44:47], v[166:169], v[208:211], v[44:47]
	v_mfma_f32_16x16x32_bf16 v[40:43], v[174:177], v[208:211], v[40:43]
	v_mfma_f32_16x16x32_bf16 v[28:31], v[166:169], v[216:219], v[28:31]
	v_mfma_f32_16x16x32_bf16 v[24:27], v[174:177], v[216:219], v[24:27]
	v_mfma_f32_16x16x32_bf16 v[12:15], v[166:169], v[224:227], v[12:15]
	v_mfma_f32_16x16x32_bf16 v[8:11], v[174:177], v[224:227], v[8:11]
	v_mfma_f32_16x16x32_bf16 v[60:63], v[170:173], v[204:207], v[60:63]
	v_mfma_f32_16x16x32_bf16 v[56:59], v[178:181], v[204:207], v[56:59]
	v_mfma_f32_16x16x32_bf16 v[44:47], v[170:173], v[212:215], v[44:47]
	v_mfma_f32_16x16x32_bf16 v[40:43], v[178:181], v[212:215], v[40:43]
	v_mfma_f32_16x16x32_bf16 v[28:31], v[170:173], v[220:223], v[28:31]
	v_mfma_f32_16x16x32_bf16 v[24:27], v[178:181], v[220:223], v[24:27]
	v_mfma_f32_16x16x32_bf16 v[12:15], v[170:173], v[228:231], v[12:15]
	v_mfma_f32_16x16x32_bf16 v[8:11], v[178:181], v[228:231], v[8:11]
	s_setprio 0
	s_setprio 1
	v_mfma_f32_16x16x32_bf16 v[52:55], v[182:185], v[200:203], v[52:55]
	v_mfma_f32_16x16x32_bf16 v[48:51], v[192:195], v[200:203], v[48:51]
	v_mfma_f32_16x16x32_bf16 v[36:39], v[182:185], v[208:211], v[36:39]
	v_mfma_f32_16x16x32_bf16 v[32:35], v[192:195], v[208:211], v[32:35]
	v_mfma_f32_16x16x32_bf16 v[20:23], v[182:185], v[216:219], v[20:23]
	v_mfma_f32_16x16x32_bf16 v[16:19], v[192:195], v[216:219], v[16:19]
	v_mfma_f32_16x16x32_bf16 v[4:7], v[182:185], v[224:227], v[4:7]
	v_mfma_f32_16x16x32_bf16 v[0:3], v[192:195], v[224:227], v[0:3]
	v_mfma_f32_16x16x32_bf16 v[52:55], v[188:191], v[204:207], v[52:55]
	v_mfma_f32_16x16x32_bf16 v[48:51], v[196:199], v[204:207], v[48:51]
	v_mfma_f32_16x16x32_bf16 v[36:39], v[188:191], v[212:215], v[36:39]
	v_mfma_f32_16x16x32_bf16 v[32:35], v[196:199], v[212:215], v[32:35]
	v_mfma_f32_16x16x32_bf16 v[20:23], v[188:191], v[220:223], v[20:23]
	v_mfma_f32_16x16x32_bf16 v[16:19], v[196:199], v[220:223], v[16:19]
	v_mfma_f32_16x16x32_bf16 v[4:7], v[188:191], v[228:231], v[4:7]
	v_mfma_f32_16x16x32_bf16 v[0:3], v[196:199], v[228:231], v[0:3]
	s_setprio 0
	s_barrier
	s_add_i32 s52, s52, 2
	s_add_u32 s42, s42, 0x100
	s_addc_u32 s43, s43, 0
	s_add_u32 s17, s17, 0x100
	s_addc_u32 s21, s21, 0
	s_cmp_gt_u32 s52, 29
	s_cbranch_scc0 .LBB0_507
	s_and_b64 vcc, exec, s[78:79]
	s_cbranch_vccz .LBB0_510
	s_barrier
